# adaLN GEMV: all 32 row loads of an item issued up front (saddr form) instead of 8 at a time
# baseline (speedup 1.0000x reference)
.LBB0_20:
	s_mul_hi_i32 s12, s38, 0x2aaaaaab
	s_lshr_b32 s13, s12, 31
	s_ashr_i32 s12, s12, 6
	s_add_i32 s20, s12, s13
	s_mul_i32 s12, s20, 0x180
	s_sub_i32 s18, s38, s12
	s_and_b32 s24, s18, 7
	s_lshl_b32 s12, s24, 8
	s_add_i32 s19, s12, s27
	s_ashr_i32 s21, s20, 31
	s_lshl_b64 s[12:13], s[20:21], 11
	s_ashr_i32 s21, s19, 31
	s_add_u32 s12, s12, s19
	s_addc_u32 s13, s13, s21
	s_mul_i32 s13, s13, 0xc000
	s_mul_hi_u32 s21, s12, 0xc000
	s_add_i32 s21, s21, s13
	s_mul_i32 s12, s12, 0xc000
	s_add_u32 s25, s56, s12
	s_addc_u32 s21, s57, s21
	s_lshl_b32 s12, s18, 5
	s_and_b32 s22, s12, 0xffffff00
	s_ashr_i32 s23, s22, 31
	s_lshl_b64 s[12:13], s[22:23], 2
	s_add_u32 s12, s25, s12
	s_addc_u32 s13, s21, s13
	s_lshl_b32 s21, s19, 2
	v_mov_b32_e32 v2, 0
	s_mov_b64 s[18:19], s[12:13]
	v_mov_b32_e32 v3, v2
	v_mov_b32_e32 v4, v2
	v_mov_b32_e32 v5, v2
	v_mov_b32_e32 v6, v2
	v_mov_b32_e32 v7, v2
	v_mov_b32_e32 v8, v2
	v_mov_b32_e32 v9, v2
	v_mov_b32_e32 v10, v2
	v_mov_b32_e32 v11, v2
	v_mov_b32_e32 v12, v2
	v_mov_b32_e32 v13, v2
.LBB0_21:
	global_load_dwordx4 v[100:103], v16, s[18:19]
	s_add_u32 s18, s18, 0xc000
	s_addc_u32 s19, s19, 0
	global_load_dwordx4 v[104:107], v16, s[18:19]
	s_add_u32 s18, s18, 0xc000
	s_addc_u32 s19, s19, 0
	global_load_dwordx4 v[108:111], v16, s[18:19]
	s_add_u32 s18, s18, 0xc000
	s_addc_u32 s19, s19, 0
	global_load_dwordx4 v[112:115], v16, s[18:19]
	s_add_u32 s18, s18, 0xc000
	s_addc_u32 s19, s19, 0
	global_load_dwordx4 v[116:119], v16, s[18:19]
	s_add_u32 s18, s18, 0xc000
	s_addc_u32 s19, s19, 0
	global_load_dwordx4 v[120:123], v16, s[18:19]
	s_add_u32 s18, s18, 0xc000
	s_addc_u32 s19, s19, 0
	global_load_dwordx4 v[124:127], v16, s[18:19]
	s_add_u32 s18, s18, 0xc000
	s_addc_u32 s19, s19, 0
	global_load_dwordx4 v[128:131], v16, s[18:19]
	s_add_u32 s18, s18, 0xc000
	s_addc_u32 s19, s19, 0
	global_load_dwordx4 v[132:135], v16, s[18:19]
	s_add_u32 s18, s18, 0xc000
	s_addc_u32 s19, s19, 0
	global_load_dwordx4 v[136:139], v16, s[18:19]
	s_add_u32 s18, s18, 0xc000
	s_addc_u32 s19, s19, 0
	global_load_dwordx4 v[140:143], v16, s[18:19]
	s_add_u32 s18, s18, 0xc000
	s_addc_u32 s19, s19, 0
	global_load_dwordx4 v[144:147], v16, s[18:19]
	s_add_u32 s18, s18, 0xc000
	s_addc_u32 s19, s19, 0
	global_load_dwordx4 v[148:151], v16, s[18:19]
	s_add_u32 s18, s18, 0xc000
	s_addc_u32 s19, s19, 0
	global_load_dwordx4 v[152:155], v16, s[18:19]
	s_add_u32 s18, s18, 0xc000
	s_addc_u32 s19, s19, 0
	global_load_dwordx4 v[156:159], v16, s[18:19]
	s_add_u32 s18, s18, 0xc000
	s_addc_u32 s19, s19, 0
	global_load_dwordx4 v[160:163], v16, s[18:19]
	s_add_u32 s18, s18, 0xc000
	s_addc_u32 s19, s19, 0
	global_load_dwordx4 v[164:167], v16, s[18:19]
	s_add_u32 s18, s18, 0xc000
	s_addc_u32 s19, s19, 0
	global_load_dwordx4 v[168:171], v16, s[18:19]
	s_add_u32 s18, s18, 0xc000
	s_addc_u32 s19, s19, 0
	global_load_dwordx4 v[172:175], v16, s[18:19]
	s_add_u32 s18, s18, 0xc000
	s_addc_u32 s19, s19, 0
	global_load_dwordx4 v[176:179], v16, s[18:19]
	s_add_u32 s18, s18, 0xc000
	s_addc_u32 s19, s19, 0
	global_load_dwordx4 v[180:183], v16, s[18:19]
	s_add_u32 s18, s18, 0xc000
	s_addc_u32 s19, s19, 0
	global_load_dwordx4 v[184:187], v16, s[18:19]
	s_add_u32 s18, s18, 0xc000
	s_addc_u32 s19, s19, 0
	global_load_dwordx4 v[188:191], v16, s[18:19]
	s_add_u32 s18, s18, 0xc000
	s_addc_u32 s19, s19, 0
	global_load_dwordx4 v[192:195], v16, s[18:19]
	s_add_u32 s18, s18, 0xc000
	s_addc_u32 s19, s19, 0
	global_load_dwordx4 v[196:199], v16, s[18:19]
	s_add_u32 s18, s18, 0xc000
	s_addc_u32 s19, s19, 0
	global_load_dwordx4 v[200:203], v16, s[18:19]
	s_add_u32 s18, s18, 0xc000
	s_addc_u32 s19, s19, 0
	global_load_dwordx4 v[204:207], v16, s[18:19]
	s_add_u32 s18, s18, 0xc000
	s_addc_u32 s19, s19, 0
	global_load_dwordx4 v[208:211], v16, s[18:19]
	s_add_u32 s18, s18, 0xc000
	s_addc_u32 s19, s19, 0
	global_load_dwordx4 v[212:215], v16, s[18:19]
	s_add_u32 s18, s18, 0xc000
	s_addc_u32 s19, s19, 0
	global_load_dwordx4 v[216:219], v16, s[18:19]
	s_add_u32 s18, s18, 0xc000
	s_addc_u32 s19, s19, 0
	global_load_dwordx4 v[220:223], v16, s[18:19]
	s_add_u32 s18, s18, 0xc000
	s_addc_u32 s19, s19, 0
	global_load_dwordx4 v[224:227], v16, s[18:19]
	v_mov_b32_e32 v80, s21
	s_add_i32 s21, s21, 32
	ds_read_b128 v[60:63], v80
	ds_read_b128 v[64:67], v80 offset:16
	ds_read_b128 v[68:71], v80 offset:8192
	ds_read_b128 v[72:75], v80 offset:8208
	ds_read_b128 v[76:79], v80 offset:16384
	ds_read_b128 v[80:83], v80 offset:16400
	s_waitcnt lgkmcnt(5)
	v_mov_b32_e32 v84, v63
	s_waitcnt lgkmcnt(3)
	v_mov_b32_e32 v86, v71
	v_mov_b32_e32 v90, v67
	s_waitcnt lgkmcnt(1)
	v_mov_b32_e32 v88, v79
	v_mov_b32_e32 v92, v75
	s_waitcnt lgkmcnt(0)
	v_mov_b32_e32 v94, v83
	s_waitcnt vmcnt(31)
	v_pk_fma_f32 v[4:5], v[102:103], v[60:61], v[4:5] op_sel_hi:[1,0,1]
	v_pk_fma_f32 v[2:3], v[100:101], v[60:61], v[2:3] op_sel_hi:[1,0,1]
	v_pk_fma_f32 v[8:9], v[102:103], v[68:69], v[8:9] op_sel_hi:[1,0,1]
	v_pk_fma_f32 v[6:7], v[100:101], v[68:69], v[6:7] op_sel_hi:[1,0,1]
	v_pk_fma_f32 v[12:13], v[102:103], v[76:77], v[12:13] op_sel_hi:[1,0,1]
	v_pk_fma_f32 v[10:11], v[100:101], v[76:77], v[10:11] op_sel_hi:[1,0,1]
	s_waitcnt vmcnt(30)
	v_pk_fma_f32 v[2:3], v[104:105], v[60:61], v[2:3] op_sel:[0,1,0]
	v_pk_fma_f32 v[4:5], v[106:107], v[60:61], v[4:5] op_sel:[0,1,0]
	v_pk_fma_f32 v[6:7], v[104:105], v[68:69], v[6:7] op_sel:[0,1,0]
	v_pk_fma_f32 v[8:9], v[106:107], v[68:69], v[8:9] op_sel:[0,1,0]
	v_pk_fma_f32 v[10:11], v[104:105], v[76:77], v[10:11] op_sel:[0,1,0]
	v_pk_fma_f32 v[12:13], v[106:107], v[76:77], v[12:13] op_sel:[0,1,0]
	s_waitcnt vmcnt(29)
	v_pk_fma_f32 v[4:5], v[110:111], v[62:63], v[4:5] op_sel_hi:[1,0,1]
	v_pk_fma_f32 v[2:3], v[108:109], v[62:63], v[2:3] op_sel_hi:[1,0,1]
	v_pk_fma_f32 v[8:9], v[110:111], v[70:71], v[8:9] op_sel_hi:[1,0,1]
	v_pk_fma_f32 v[6:7], v[108:109], v[70:71], v[6:7] op_sel_hi:[1,0,1]
	v_pk_fma_f32 v[12:13], v[110:111], v[78:79], v[12:13] op_sel_hi:[1,0,1]
	v_pk_fma_f32 v[10:11], v[108:109], v[78:79], v[10:11] op_sel_hi:[1,0,1]
	s_waitcnt vmcnt(28)
	v_pk_fma_f32 v[4:5], v[114:115], v[84:85], v[4:5] op_sel_hi:[1,0,1]
	v_pk_fma_f32 v[2:3], v[112:113], v[84:85], v[2:3] op_sel_hi:[1,0,1]
	v_pk_fma_f32 v[8:9], v[114:115], v[86:87], v[8:9] op_sel_hi:[1,0,1]
	v_pk_fma_f32 v[6:7], v[112:113], v[86:87], v[6:7] op_sel_hi:[1,0,1]
	v_pk_fma_f32 v[12:13], v[114:115], v[88:89], v[12:13] op_sel_hi:[1,0,1]
	v_pk_fma_f32 v[10:11], v[112:113], v[88:89], v[10:11] op_sel_hi:[1,0,1]
	s_waitcnt vmcnt(27)
	v_pk_fma_f32 v[4:5], v[118:119], v[64:65], v[4:5] op_sel_hi:[1,0,1]
	v_pk_fma_f32 v[2:3], v[116:117], v[64:65], v[2:3] op_sel_hi:[1,0,1]
	v_pk_fma_f32 v[8:9], v[118:119], v[72:73], v[8:9] op_sel_hi:[1,0,1]
	v_pk_fma_f32 v[6:7], v[116:117], v[72:73], v[6:7] op_sel_hi:[1,0,1]
	v_pk_fma_f32 v[12:13], v[118:119], v[80:81], v[12:13] op_sel_hi:[1,0,1]
	v_pk_fma_f32 v[10:11], v[116:117], v[80:81], v[10:11] op_sel_hi:[1,0,1]
	s_waitcnt vmcnt(26)
	v_pk_fma_f32 v[4:5], v[122:123], v[64:65], v[4:5] op_sel:[0,1,0]
	v_pk_fma_f32 v[2:3], v[120:121], v[64:65], v[2:3] op_sel:[0,1,0]
	v_pk_fma_f32 v[8:9], v[122:123], v[72:73], v[8:9] op_sel:[0,1,0]
	v_pk_fma_f32 v[6:7], v[120:121], v[72:73], v[6:7] op_sel:[0,1,0]
	v_pk_fma_f32 v[12:13], v[122:123], v[80:81], v[12:13] op_sel:[0,1,0]
	v_pk_fma_f32 v[10:11], v[120:121], v[80:81], v[10:11] op_sel:[0,1,0]
	s_waitcnt vmcnt(25)
	v_pk_fma_f32 v[4:5], v[126:127], v[66:67], v[4:5] op_sel_hi:[1,0,1]
	v_pk_fma_f32 v[2:3], v[124:125], v[66:67], v[2:3] op_sel_hi:[1,0,1]
	v_pk_fma_f32 v[8:9], v[126:127], v[74:75], v[8:9] op_sel_hi:[1,0,1]
	v_pk_fma_f32 v[6:7], v[124:125], v[74:75], v[6:7] op_sel_hi:[1,0,1]
	v_pk_fma_f32 v[12:13], v[126:127], v[82:83], v[12:13] op_sel_hi:[1,0,1]
	v_pk_fma_f32 v[10:11], v[124:125], v[82:83], v[10:11] op_sel_hi:[1,0,1]
	s_waitcnt vmcnt(24)
	v_pk_fma_f32 v[4:5], v[130:131], v[90:91], v[4:5] op_sel_hi:[1,0,1]
	v_pk_fma_f32 v[2:3], v[128:129], v[90:91], v[2:3] op_sel_hi:[1,0,1]
	v_pk_fma_f32 v[8:9], v[130:131], v[92:93], v[8:9] op_sel_hi:[1,0,1]
	v_pk_fma_f32 v[6:7], v[128:129], v[92:93], v[6:7] op_sel_hi:[1,0,1]
	v_pk_fma_f32 v[12:13], v[130:131], v[94:95], v[12:13] op_sel_hi:[1,0,1]
	v_pk_fma_f32 v[10:11], v[128:129], v[94:95], v[10:11] op_sel_hi:[1,0,1]
	v_mov_b32_e32 v80, s21
	s_add_i32 s21, s21, 32
	ds_read_b128 v[60:63], v80
	ds_read_b128 v[64:67], v80 offset:16
	ds_read_b128 v[68:71], v80 offset:8192
	ds_read_b128 v[72:75], v80 offset:8208
	ds_read_b128 v[76:79], v80 offset:16384
	ds_read_b128 v[80:83], v80 offset:16400
	s_waitcnt lgkmcnt(5)
	v_mov_b32_e32 v84, v63
	s_waitcnt lgkmcnt(3)
	v_mov_b32_e32 v86, v71
	v_mov_b32_e32 v90, v67
	s_waitcnt lgkmcnt(1)
	v_mov_b32_e32 v88, v79
	v_mov_b32_e32 v92, v75
	s_waitcnt lgkmcnt(0)
	v_mov_b32_e32 v94, v83
	s_waitcnt vmcnt(23)
	v_pk_fma_f32 v[4:5], v[134:135], v[60:61], v[4:5] op_sel_hi:[1,0,1]
	v_pk_fma_f32 v[2:3], v[132:133], v[60:61], v[2:3] op_sel_hi:[1,0,1]
	v_pk_fma_f32 v[8:9], v[134:135], v[68:69], v[8:9] op_sel_hi:[1,0,1]
	v_pk_fma_f32 v[6:7], v[132:133], v[68:69], v[6:7] op_sel_hi:[1,0,1]
	v_pk_fma_f32 v[12:13], v[134:135], v[76:77], v[12:13] op_sel_hi:[1,0,1]
	v_pk_fma_f32 v[10:11], v[132:133], v[76:77], v[10:11] op_sel_hi:[1,0,1]
	s_waitcnt vmcnt(22)
	v_pk_fma_f32 v[2:3], v[136:137], v[60:61], v[2:3] op_sel:[0,1,0]
	v_pk_fma_f32 v[4:5], v[138:139], v[60:61], v[4:5] op_sel:[0,1,0]
	v_pk_fma_f32 v[6:7], v[136:137], v[68:69], v[6:7] op_sel:[0,1,0]
	v_pk_fma_f32 v[8:9], v[138:139], v[68:69], v[8:9] op_sel:[0,1,0]
	v_pk_fma_f32 v[10:11], v[136:137], v[76:77], v[10:11] op_sel:[0,1,0]
	v_pk_fma_f32 v[12:13], v[138:139], v[76:77], v[12:13] op_sel:[0,1,0]
	s_waitcnt vmcnt(21)
	v_pk_fma_f32 v[4:5], v[142:143], v[62:63], v[4:5] op_sel_hi:[1,0,1]
	v_pk_fma_f32 v[2:3], v[140:141], v[62:63], v[2:3] op_sel_hi:[1,0,1]
	v_pk_fma_f32 v[8:9], v[142:143], v[70:71], v[8:9] op_sel_hi:[1,0,1]
	v_pk_fma_f32 v[6:7], v[140:141], v[70:71], v[6:7] op_sel_hi:[1,0,1]
	v_pk_fma_f32 v[12:13], v[142:143], v[78:79], v[12:13] op_sel_hi:[1,0,1]
	v_pk_fma_f32 v[10:11], v[140:141], v[78:79], v[10:11] op_sel_hi:[1,0,1]
	s_waitcnt vmcnt(20)
	v_pk_fma_f32 v[4:5], v[146:147], v[84:85], v[4:5] op_sel_hi:[1,0,1]
	v_pk_fma_f32 v[2:3], v[144:145], v[84:85], v[2:3] op_sel_hi:[1,0,1]
	v_pk_fma_f32 v[8:9], v[146:147], v[86:87], v[8:9] op_sel_hi:[1,0,1]
	v_pk_fma_f32 v[6:7], v[144:145], v[86:87], v[6:7] op_sel_hi:[1,0,1]
	v_pk_fma_f32 v[12:13], v[146:147], v[88:89], v[12:13] op_sel_hi:[1,0,1]
	v_pk_fma_f32 v[10:11], v[144:145], v[88:89], v[10:11] op_sel_hi:[1,0,1]
	s_waitcnt vmcnt(19)
	v_pk_fma_f32 v[4:5], v[150:151], v[64:65], v[4:5] op_sel_hi:[1,0,1]
	v_pk_fma_f32 v[2:3], v[148:149], v[64:65], v[2:3] op_sel_hi:[1,0,1]
	v_pk_fma_f32 v[8:9], v[150:151], v[72:73], v[8:9] op_sel_hi:[1,0,1]
	v_pk_fma_f32 v[6:7], v[148:149], v[72:73], v[6:7] op_sel_hi:[1,0,1]
	v_pk_fma_f32 v[12:13], v[150:151], v[80:81], v[12:13] op_sel_hi:[1,0,1]
	v_pk_fma_f32 v[10:11], v[148:149], v[80:81], v[10:11] op_sel_hi:[1,0,1]
	s_waitcnt vmcnt(18)
	v_pk_fma_f32 v[4:5], v[154:155], v[64:65], v[4:5] op_sel:[0,1,0]
	v_pk_fma_f32 v[2:3], v[152:153], v[64:65], v[2:3] op_sel:[0,1,0]
	v_pk_fma_f32 v[8:9], v[154:155], v[72:73], v[8:9] op_sel:[0,1,0]
	v_pk_fma_f32 v[6:7], v[152:153], v[72:73], v[6:7] op_sel:[0,1,0]
	v_pk_fma_f32 v[12:13], v[154:155], v[80:81], v[12:13] op_sel:[0,1,0]
	v_pk_fma_f32 v[10:11], v[152:153], v[80:81], v[10:11] op_sel:[0,1,0]
	s_waitcnt vmcnt(17)
	v_pk_fma_f32 v[4:5], v[158:159], v[66:67], v[4:5] op_sel_hi:[1,0,1]
	v_pk_fma_f32 v[2:3], v[156:157], v[66:67], v[2:3] op_sel_hi:[1,0,1]
	v_pk_fma_f32 v[8:9], v[158:159], v[74:75], v[8:9] op_sel_hi:[1,0,1]
	v_pk_fma_f32 v[6:7], v[156:157], v[74:75], v[6:7] op_sel_hi:[1,0,1]
	v_pk_fma_f32 v[12:13], v[158:159], v[82:83], v[12:13] op_sel_hi:[1,0,1]
	v_pk_fma_f32 v[10:11], v[156:157], v[82:83], v[10:11] op_sel_hi:[1,0,1]
	s_waitcnt vmcnt(16)
	v_pk_fma_f32 v[4:5], v[162:163], v[90:91], v[4:5] op_sel_hi:[1,0,1]
	v_pk_fma_f32 v[2:3], v[160:161], v[90:91], v[2:3] op_sel_hi:[1,0,1]
	v_pk_fma_f32 v[8:9], v[162:163], v[92:93], v[8:9] op_sel_hi:[1,0,1]
	v_pk_fma_f32 v[6:7], v[160:161], v[92:93], v[6:7] op_sel_hi:[1,0,1]
	v_pk_fma_f32 v[12:13], v[162:163], v[94:95], v[12:13] op_sel_hi:[1,0,1]
	v_pk_fma_f32 v[10:11], v[160:161], v[94:95], v[10:11] op_sel_hi:[1,0,1]
	v_mov_b32_e32 v80, s21
	s_add_i32 s21, s21, 32
	ds_read_b128 v[60:63], v80
	ds_read_b128 v[64:67], v80 offset:16
	ds_read_b128 v[68:71], v80 offset:8192
	ds_read_b128 v[72:75], v80 offset:8208
	ds_read_b128 v[76:79], v80 offset:16384
	ds_read_b128 v[80:83], v80 offset:16400
	s_waitcnt lgkmcnt(5)
	v_mov_b32_e32 v84, v63
	s_waitcnt lgkmcnt(3)
	v_mov_b32_e32 v86, v71
	v_mov_b32_e32 v90, v67
	s_waitcnt lgkmcnt(1)
	v_mov_b32_e32 v88, v79
	v_mov_b32_e32 v92, v75
	s_waitcnt lgkmcnt(0)
	v_mov_b32_e32 v94, v83
	s_waitcnt vmcnt(15)
	v_pk_fma_f32 v[4:5], v[166:167], v[60:61], v[4:5] op_sel_hi:[1,0,1]
	v_pk_fma_f32 v[2:3], v[164:165], v[60:61], v[2:3] op_sel_hi:[1,0,1]
	v_pk_fma_f32 v[8:9], v[166:167], v[68:69], v[8:9] op_sel_hi:[1,0,1]
	v_pk_fma_f32 v[6:7], v[164:165], v[68:69], v[6:7] op_sel_hi:[1,0,1]
	v_pk_fma_f32 v[12:13], v[166:167], v[76:77], v[12:13] op_sel_hi:[1,0,1]
	v_pk_fma_f32 v[10:11], v[164:165], v[76:77], v[10:11] op_sel_hi:[1,0,1]
	s_waitcnt vmcnt(14)
	v_pk_fma_f32 v[2:3], v[168:169], v[60:61], v[2:3] op_sel:[0,1,0]
	v_pk_fma_f32 v[4:5], v[170:171], v[60:61], v[4:5] op_sel:[0,1,0]
	v_pk_fma_f32 v[6:7], v[168:169], v[68:69], v[6:7] op_sel:[0,1,0]
	v_pk_fma_f32 v[8:9], v[170:171], v[68:69], v[8:9] op_sel:[0,1,0]
	v_pk_fma_f32 v[10:11], v[168:169], v[76:77], v[10:11] op_sel:[0,1,0]
	v_pk_fma_f32 v[12:13], v[170:171], v[76:77], v[12:13] op_sel:[0,1,0]
	s_waitcnt vmcnt(13)
	v_pk_fma_f32 v[4:5], v[174:175], v[62:63], v[4:5] op_sel_hi:[1,0,1]
	v_pk_fma_f32 v[2:3], v[172:173], v[62:63], v[2:3] op_sel_hi:[1,0,1]
	v_pk_fma_f32 v[8:9], v[174:175], v[70:71], v[8:9] op_sel_hi:[1,0,1]
	v_pk_fma_f32 v[6:7], v[172:173], v[70:71], v[6:7] op_sel_hi:[1,0,1]
	v_pk_fma_f32 v[12:13], v[174:175], v[78:79], v[12:13] op_sel_hi:[1,0,1]
	v_pk_fma_f32 v[10:11], v[172:173], v[78:79], v[10:11] op_sel_hi:[1,0,1]
	s_waitcnt vmcnt(12)
	v_pk_fma_f32 v[4:5], v[178:179], v[84:85], v[4:5] op_sel_hi:[1,0,1]
	v_pk_fma_f32 v[2:3], v[176:177], v[84:85], v[2:3] op_sel_hi:[1,0,1]
	v_pk_fma_f32 v[8:9], v[178:179], v[86:87], v[8:9] op_sel_hi:[1,0,1]
	v_pk_fma_f32 v[6:7], v[176:177], v[86:87], v[6:7] op_sel_hi:[1,0,1]
	v_pk_fma_f32 v[12:13], v[178:179], v[88:89], v[12:13] op_sel_hi:[1,0,1]
	v_pk_fma_f32 v[10:11], v[176:177], v[88:89], v[10:11] op_sel_hi:[1,0,1]
	s_waitcnt vmcnt(11)
	v_pk_fma_f32 v[4:5], v[182:183], v[64:65], v[4:5] op_sel_hi:[1,0,1]
	v_pk_fma_f32 v[2:3], v[180:181], v[64:65], v[2:3] op_sel_hi:[1,0,1]
	v_pk_fma_f32 v[8:9], v[182:183], v[72:73], v[8:9] op_sel_hi:[1,0,1]
	v_pk_fma_f32 v[6:7], v[180:181], v[72:73], v[6:7] op_sel_hi:[1,0,1]
	v_pk_fma_f32 v[12:13], v[182:183], v[80:81], v[12:13] op_sel_hi:[1,0,1]
	v_pk_fma_f32 v[10:11], v[180:181], v[80:81], v[10:11] op_sel_hi:[1,0,1]
	s_waitcnt vmcnt(10)
	v_pk_fma_f32 v[4:5], v[186:187], v[64:65], v[4:5] op_sel:[0,1,0]
	v_pk_fma_f32 v[2:3], v[184:185], v[64:65], v[2:3] op_sel:[0,1,0]
	v_pk_fma_f32 v[8:9], v[186:187], v[72:73], v[8:9] op_sel:[0,1,0]
	v_pk_fma_f32 v[6:7], v[184:185], v[72:73], v[6:7] op_sel:[0,1,0]
	v_pk_fma_f32 v[12:13], v[186:187], v[80:81], v[12:13] op_sel:[0,1,0]
	v_pk_fma_f32 v[10:11], v[184:185], v[80:81], v[10:11] op_sel:[0,1,0]
	s_waitcnt vmcnt(9)
	v_pk_fma_f32 v[4:5], v[190:191], v[66:67], v[4:5] op_sel_hi:[1,0,1]
	v_pk_fma_f32 v[2:3], v[188:189], v[66:67], v[2:3] op_sel_hi:[1,0,1]
	v_pk_fma_f32 v[8:9], v[190:191], v[74:75], v[8:9] op_sel_hi:[1,0,1]
	v_pk_fma_f32 v[6:7], v[188:189], v[74:75], v[6:7] op_sel_hi:[1,0,1]
	v_pk_fma_f32 v[12:13], v[190:191], v[82:83], v[12:13] op_sel_hi:[1,0,1]
	v_pk_fma_f32 v[10:11], v[188:189], v[82:83], v[10:11] op_sel_hi:[1,0,1]
	s_waitcnt vmcnt(8)
	v_pk_fma_f32 v[4:5], v[194:195], v[90:91], v[4:5] op_sel_hi:[1,0,1]
	v_pk_fma_f32 v[2:3], v[192:193], v[90:91], v[2:3] op_sel_hi:[1,0,1]
	v_pk_fma_f32 v[8:9], v[194:195], v[92:93], v[8:9] op_sel_hi:[1,0,1]
	v_pk_fma_f32 v[6:7], v[192:193], v[92:93], v[6:7] op_sel_hi:[1,0,1]
	v_pk_fma_f32 v[12:13], v[194:195], v[94:95], v[12:13] op_sel_hi:[1,0,1]
	v_pk_fma_f32 v[10:11], v[192:193], v[94:95], v[10:11] op_sel_hi:[1,0,1]
	v_mov_b32_e32 v80, s21
	s_add_i32 s21, s21, 32
	ds_read_b128 v[60:63], v80
	ds_read_b128 v[64:67], v80 offset:16
	ds_read_b128 v[68:71], v80 offset:8192
	ds_read_b128 v[72:75], v80 offset:8208
	ds_read_b128 v[76:79], v80 offset:16384
	ds_read_b128 v[80:83], v80 offset:16400
	s_waitcnt lgkmcnt(5)
	v_mov_b32_e32 v84, v63
	s_waitcnt lgkmcnt(3)
	v_mov_b32_e32 v86, v71
	v_mov_b32_e32 v90, v67
	s_waitcnt lgkmcnt(1)
	v_mov_b32_e32 v88, v79
	v_mov_b32_e32 v92, v75
	s_waitcnt lgkmcnt(0)
	v_mov_b32_e32 v94, v83
	s_waitcnt vmcnt(7)
	v_pk_fma_f32 v[4:5], v[198:199], v[60:61], v[4:5] op_sel_hi:[1,0,1]
	v_pk_fma_f32 v[2:3], v[196:197], v[60:61], v[2:3] op_sel_hi:[1,0,1]
	v_pk_fma_f32 v[8:9], v[198:199], v[68:69], v[8:9] op_sel_hi:[1,0,1]
	v_pk_fma_f32 v[6:7], v[196:197], v[68:69], v[6:7] op_sel_hi:[1,0,1]
	v_pk_fma_f32 v[12:13], v[198:199], v[76:77], v[12:13] op_sel_hi:[1,0,1]
	v_pk_fma_f32 v[10:11], v[196:197], v[76:77], v[10:11] op_sel_hi:[1,0,1]
	s_waitcnt vmcnt(6)
	v_pk_fma_f32 v[2:3], v[200:201], v[60:61], v[2:3] op_sel:[0,1,0]
	v_pk_fma_f32 v[4:5], v[202:203], v[60:61], v[4:5] op_sel:[0,1,0]
	v_pk_fma_f32 v[6:7], v[200:201], v[68:69], v[6:7] op_sel:[0,1,0]
	v_pk_fma_f32 v[8:9], v[202:203], v[68:69], v[8:9] op_sel:[0,1,0]
	v_pk_fma_f32 v[10:11], v[200:201], v[76:77], v[10:11] op_sel:[0,1,0]
	v_pk_fma_f32 v[12:13], v[202:203], v[76:77], v[12:13] op_sel:[0,1,0]
	s_waitcnt vmcnt(5)
	v_pk_fma_f32 v[4:5], v[206:207], v[62:63], v[4:5] op_sel_hi:[1,0,1]
	v_pk_fma_f32 v[2:3], v[204:205], v[62:63], v[2:3] op_sel_hi:[1,0,1]
	v_pk_fma_f32 v[8:9], v[206:207], v[70:71], v[8:9] op_sel_hi:[1,0,1]
	v_pk_fma_f32 v[6:7], v[204:205], v[70:71], v[6:7] op_sel_hi:[1,0,1]
	v_pk_fma_f32 v[12:13], v[206:207], v[78:79], v[12:13] op_sel_hi:[1,0,1]
	v_pk_fma_f32 v[10:11], v[204:205], v[78:79], v[10:11] op_sel_hi:[1,0,1]
	s_waitcnt vmcnt(4)
	v_pk_fma_f32 v[4:5], v[210:211], v[84:85], v[4:5] op_sel_hi:[1,0,1]
	v_pk_fma_f32 v[2:3], v[208:209], v[84:85], v[2:3] op_sel_hi:[1,0,1]
	v_pk_fma_f32 v[8:9], v[210:211], v[86:87], v[8:9] op_sel_hi:[1,0,1]
	v_pk_fma_f32 v[6:7], v[208:209], v[86:87], v[6:7] op_sel_hi:[1,0,1]
	v_pk_fma_f32 v[12:13], v[210:211], v[88:89], v[12:13] op_sel_hi:[1,0,1]
	v_pk_fma_f32 v[10:11], v[208:209], v[88:89], v[10:11] op_sel_hi:[1,0,1]
	s_waitcnt vmcnt(3)
	v_pk_fma_f32 v[4:5], v[214:215], v[64:65], v[4:5] op_sel_hi:[1,0,1]
	v_pk_fma_f32 v[2:3], v[212:213], v[64:65], v[2:3] op_sel_hi:[1,0,1]
	v_pk_fma_f32 v[8:9], v[214:215], v[72:73], v[8:9] op_sel_hi:[1,0,1]
	v_pk_fma_f32 v[6:7], v[212:213], v[72:73], v[6:7] op_sel_hi:[1,0,1]
	v_pk_fma_f32 v[12:13], v[214:215], v[80:81], v[12:13] op_sel_hi:[1,0,1]
	v_pk_fma_f32 v[10:11], v[212:213], v[80:81], v[10:11] op_sel_hi:[1,0,1]
	s_waitcnt vmcnt(2)
	v_pk_fma_f32 v[4:5], v[218:219], v[64:65], v[4:5] op_sel:[0,1,0]
	v_pk_fma_f32 v[2:3], v[216:217], v[64:65], v[2:3] op_sel:[0,1,0]
	v_pk_fma_f32 v[8:9], v[218:219], v[72:73], v[8:9] op_sel:[0,1,0]
	v_pk_fma_f32 v[6:7], v[216:217], v[72:73], v[6:7] op_sel:[0,1,0]
	v_pk_fma_f32 v[12:13], v[218:219], v[80:81], v[12:13] op_sel:[0,1,0]
	v_pk_fma_f32 v[10:11], v[216:217], v[80:81], v[10:11] op_sel:[0,1,0]
	s_waitcnt vmcnt(1)
	v_pk_fma_f32 v[4:5], v[222:223], v[66:67], v[4:5] op_sel_hi:[1,0,1]
	v_pk_fma_f32 v[2:3], v[220:221], v[66:67], v[2:3] op_sel_hi:[1,0,1]
	v_pk_fma_f32 v[8:9], v[222:223], v[74:75], v[8:9] op_sel_hi:[1,0,1]
	v_pk_fma_f32 v[6:7], v[220:221], v[74:75], v[6:7] op_sel_hi:[1,0,1]
	v_pk_fma_f32 v[12:13], v[222:223], v[82:83], v[12:13] op_sel_hi:[1,0,1]
	v_pk_fma_f32 v[10:11], v[220:221], v[82:83], v[10:11] op_sel_hi:[1,0,1]
	s_waitcnt vmcnt(0)
	v_pk_fma_f32 v[4:5], v[226:227], v[90:91], v[4:5] op_sel_hi:[1,0,1]
	v_pk_fma_f32 v[2:3], v[224:225], v[90:91], v[2:3] op_sel_hi:[1,0,1]
	v_pk_fma_f32 v[8:9], v[226:227], v[92:93], v[8:9] op_sel_hi:[1,0,1]
	v_pk_fma_f32 v[6:7], v[224:225], v[92:93], v[6:7] op_sel_hi:[1,0,1]
	v_pk_fma_f32 v[12:13], v[226:227], v[94:95], v[12:13] op_sel_hi:[1,0,1]
	v_pk_fma_f32 v[10:11], v[224:225], v[94:95], v[10:11] op_sel_hi:[1,0,1]
	ds_write_b128 v24, v[2:5] offset:24576
	ds_write_b128 v24, v[6:9] offset:25600
	ds_write_b128 v24, v[10:13] offset:26624
	s_waitcnt lgkmcnt(0)
	s_barrier
	s_and_saveexec_b64 s[18:19], vcc
	s_cbranch_execz .LBB0_19
	s_lshl_b32 s12, s24, 2
	s_add_i32 s39, s12, s20
	s_mul_i32 s39, s39, 3
	v_lshl_add_u64 v[2:3], s[22:23], 2, v[18:19]
	s_mov_b64 s[12:13], -1
	v_mov_b32_e32 v4, v14
	s_and_saveexec_b64 s[20:21], s[10:11]
	s_cbranch_execz .LBB0_31
	v_mov_b64_e32 v[4:5], v[14:15]
	s_and_saveexec_b64 s[22:23], s[4:5]
	s_cbranch_execz .LBB0_28
	s_mov_b64 s[24:25], 0
	v_mov_b32_e32 v6, v27
	v_mov_b64_e32 v[4:5], v[14:15]
